# stacked small edits on v5: Y-part LDS writes spread, retention micro-loop reads ahead, in-proj copy-out 4 reads in flight, attention mask precompute only on masked key tiles
# speedup vs baseline: 1.0804x; 1.0027x over previous
.LBB0_548:
	v_add_u32_e32 v3, s0, v1
	v_ashrrev_i32_e32 v10, 5, v3
	v_mad_u64_u32 v[6:7], s[8:9], v10, s3, v[2:3]
	ds_read_b128 v[146:149], v6
	ds_read_b128 v[150:153], v6 offset:8448
	ds_read_b128 v[154:157], v6 offset:16896
	ds_read_b128 v[158:161], v6 offset:25344
	v_add_u32_e32 v10, s6, v10
	v_mad_i64_i32 v[162:163], s[8:9], v10, s97, v[4:5]
	v_add_u32_e32 v11, 16, v10
	v_mad_i64_i32 v[164:165], s[8:9], v11, s97, v[4:5]
	v_add_u32_e32 v11, 32, v10
	v_mad_i64_i32 v[166:167], s[8:9], v11, s97, v[4:5]
	v_add_u32_e32 v11, 48, v10
	v_mad_i64_i32 v[168:169], s[8:9], v11, s97, v[4:5]
	s_addk_i32 s0, 0x800
	s_cmpk_lg_i32 s0, 0x2000
	s_waitcnt lgkmcnt(3)
	global_store_dwordx4 v[162:163], v[146:149], off
	s_waitcnt lgkmcnt(2)
	global_store_dwordx4 v[164:165], v[150:153], off
	s_waitcnt lgkmcnt(1)
	global_store_dwordx4 v[166:167], v[154:157], off
	s_waitcnt lgkmcnt(0)
	global_store_dwordx4 v[168:169], v[158:161], off
	s_cbranch_scc1 .LBB0_548
	s_add_i32 s20, s20, s74
	s_cmpk_lt_i32 s20, 0x900
	s_cbranch_scc1 .LBB0_278
	s_branch .LBB0_552

.LBB0_630:
	s_andn2_b64 vcc, exec, s[0:1]
	s_cbranch_vccnz .LBB0_632
	v_add_u32_e32 v203, s72, v172
	v_add_u32_e32 v248, 0xffffff80, v203
	v_add_u32_e32 v247, 0xffffff81, v203
	v_add_u32_e32 v246, 0xffffff82, v203
	v_add_u32_e32 v245, 0xffffff83, v203
	v_add_u32_e32 v244, 0xffffff88, v203
	v_add_u32_e32 v243, 0xffffff89, v203
	v_add_u32_e32 v242, 0xffffff8a, v203
	v_add_u32_e32 v241, 0xffffff8b, v203
	v_add_u32_e32 v240, 0xffffff90, v203
	v_add_u32_e32 v239, 0xffffff91, v203
	v_add_u32_e32 v238, 0xffffff92, v203
	v_add_u32_e32 v237, 0xffffff93, v203
	v_add_u32_e32 v236, 0xffffff98, v203
	v_add_u32_e32 v235, 0xffffff99, v203
	v_add_u32_e32 v234, 0xffffff9a, v203
	v_add_u32_e32 v233, 0xffffff9b, v203
	v_add_u32_e32 v232, 0xffffffa0, v203
	v_add_u32_e32 v231, 0xffffffa1, v203
	v_add_u32_e32 v230, 0xffffffa2, v203
	v_add_u32_e32 v229, 0xffffffa3, v203
	v_add_u32_e32 v228, 0xffffffa8, v203
	v_add_u32_e32 v227, 0xffffffa9, v203
	v_add_u32_e32 v226, 0xffffffaa, v203
	v_add_u32_e32 v225, 0xffffffab, v203
	v_add_u32_e32 v224, 0xffffffb0, v203
	v_add_u32_e32 v223, 0xffffffb1, v203
	v_add_u32_e32 v209, 0xffffffb2, v203
	v_add_u32_e32 v208, 0xffffffb3, v203
	v_add_u32_e32 v207, 0xffffffb8, v203
	v_add_u32_e32 v206, 0xffffffb9, v203
	v_add_u32_e32 v205, 0xffffffba, v203
	v_add_u32_e32 v203, 0xffffffbb, v203
	v_cmp_gt_i32_e64 s[64:65], s71, v248
	v_add_u32_e32 v204, s74, v188
	v_cmp_gt_i32_e64 s[62:63], s71, v247
	v_cmp_gt_i32_e64 s[60:61], s71, v246
	v_cmp_gt_i32_e64 s[58:59], s71, v245
	v_cmp_gt_i32_e64 s[56:57], s71, v244
	v_cmp_gt_i32_e64 s[54:55], s71, v243
	v_cmp_gt_i32_e64 s[52:53], s71, v242
	v_cmp_gt_i32_e64 s[50:51], s71, v241
	v_cmp_gt_i32_e64 s[48:49], s71, v240
	v_cmp_gt_i32_e64 s[46:47], s71, v239
	v_cmp_gt_i32_e64 s[44:45], s71, v238
	v_cmp_gt_i32_e64 s[42:43], s71, v237
	v_cmp_gt_i32_e64 s[40:41], s71, v236
	v_cmp_gt_i32_e64 s[38:39], s71, v235
	v_cmp_gt_i32_e64 s[36:37], s71, v234
	v_cmp_gt_i32_e64 s[34:35], s71, v233
	v_cmp_gt_i32_e64 s[30:31], s71, v232
	v_cmp_gt_i32_e64 s[28:29], s71, v231
	v_cmp_gt_i32_e64 s[26:27], s71, v230
	v_cmp_gt_i32_e64 s[24:25], s71, v229
	v_cmp_gt_i32_e64 s[22:23], s71, v228
	v_cmp_gt_i32_e64 s[20:21], s71, v227
	v_cmp_gt_i32_e64 s[18:19], s71, v226
	v_cmp_gt_i32_e64 s[16:17], s71, v225
	v_cmp_gt_i32_e64 s[14:15], s71, v224
	v_cmp_gt_i32_e64 s[12:13], s71, v223
	v_cmp_gt_i32_e64 s[10:11], s71, v209
	v_cmp_gt_i32_e64 s[8:9], s71, v208
	v_cmp_gt_i32_e64 s[6:7], s71, v207
	v_cmp_gt_i32_e64 s[4:5], s71, v206
	v_cmp_gt_i32_e64 s[66:67], s71, v205
	v_cmp_gt_i32_e64 s[0:1], s71, v203
	v_add_u32_e32 v201, 0x100, v204
	v_cmp_gt_u32_e32 vcc, s75, v201
	s_and_b64 s[64:65], s[92:93], s[64:65]
	s_and_b64 vcc, s[64:65], vcc
	v_add_u32_e32 v201, 0xff, v204
	v_cndmask_b32_e32 v114, v221, v114, vcc
	v_cmp_gt_u32_e32 vcc, s75, v201
	s_and_b64 s[62:63], s[92:93], s[62:63]
	s_and_b64 vcc, s[62:63], vcc
	v_add_u32_e32 v212, 0xfe, v204
	v_cndmask_b32_e32 v115, v221, v115, vcc
	v_cmp_gt_u32_e32 vcc, s75, v212
	s_and_b64 s[60:61], s[92:93], s[60:61]
	s_and_b64 vcc, s[60:61], vcc
	v_add_u32_e32 v212, 0xfd, v204
	v_cndmask_b32_e32 v116, v221, v116, vcc
	v_cmp_gt_u32_e32 vcc, s75, v212
	s_and_b64 s[58:59], s[92:93], s[58:59]
	s_and_b64 vcc, s[58:59], vcc
	v_add_u32_e32 v212, 0xf8, v204
	v_cndmask_b32_e32 v117, v221, v117, vcc
	v_cmp_gt_u32_e32 vcc, s75, v212
	s_and_b64 s[56:57], s[92:93], s[56:57]
	s_and_b64 vcc, s[56:57], vcc
	v_add_u32_e32 v212, 0xf7, v204
	v_cndmask_b32_e32 v118, v221, v118, vcc
	v_cmp_gt_u32_e32 vcc, s75, v212
	s_and_b64 s[54:55], s[92:93], s[54:55]
	s_and_b64 vcc, s[54:55], vcc
	v_add_u32_e32 v212, 0xf6, v204
	v_cndmask_b32_e32 v119, v221, v119, vcc
	v_cmp_gt_u32_e32 vcc, s75, v212
	s_and_b64 s[52:53], s[92:93], s[52:53]
	s_and_b64 vcc, s[52:53], vcc
	v_add_u32_e32 v212, 0xf5, v204
	v_cndmask_b32_e32 v120, v221, v120, vcc
	v_cmp_gt_u32_e32 vcc, s75, v212
	s_and_b64 s[50:51], s[92:93], s[50:51]
	s_and_b64 vcc, s[50:51], vcc
	v_add_u32_e32 v212, 0xf0, v204
	v_cndmask_b32_e32 v121, v221, v121, vcc
	v_cmp_gt_u32_e32 vcc, s75, v212
	s_and_b64 s[48:49], s[92:93], s[48:49]
	s_and_b64 vcc, s[48:49], vcc
	v_add_u32_e32 v212, 0xef, v204
	v_cndmask_b32_e32 v122, v221, v122, vcc
	v_cmp_gt_u32_e32 vcc, s75, v212
	s_and_b64 s[46:47], s[92:93], s[46:47]
	s_and_b64 vcc, s[46:47], vcc
	v_add_u32_e32 v212, 0xee, v204
	v_cndmask_b32_e32 v123, v221, v123, vcc
	v_cmp_gt_u32_e32 vcc, s75, v212
	s_and_b64 s[44:45], s[92:93], s[44:45]
	s_and_b64 vcc, s[44:45], vcc
	v_add_u32_e32 v212, 0xed, v204
	v_cndmask_b32_e32 v124, v221, v124, vcc
	v_cmp_gt_u32_e32 vcc, s75, v212
	s_and_b64 s[42:43], s[92:93], s[42:43]
	s_and_b64 vcc, s[42:43], vcc
	v_add_u32_e32 v212, 0xe8, v204
	v_cndmask_b32_e32 v125, v221, v125, vcc
	v_cmp_gt_u32_e32 vcc, s75, v212
	s_and_b64 s[40:41], s[92:93], s[40:41]
	s_and_b64 vcc, s[40:41], vcc
	v_add_u32_e32 v212, 0xe7, v204
	v_cndmask_b32_e32 v126, v221, v126, vcc
	v_cmp_gt_u32_e32 vcc, s75, v212
	s_and_b64 s[38:39], s[92:93], s[38:39]
	s_and_b64 vcc, s[38:39], vcc
	v_add_u32_e32 v212, 0xe6, v204
	v_cndmask_b32_e32 v127, v221, v127, vcc
	v_cmp_gt_u32_e32 vcc, s75, v212
	s_and_b64 s[36:37], s[92:93], s[36:37]
	s_and_b64 vcc, s[36:37], vcc
	v_add_u32_e32 v212, 0xe5, v204
	v_cndmask_b32_e32 v128, v221, v128, vcc
	v_cmp_gt_u32_e32 vcc, s75, v212
	s_and_b64 s[34:35], s[92:93], s[34:35]
	s_and_b64 vcc, s[34:35], vcc
	v_add_u32_e32 v212, 0xe0, v204
	v_cndmask_b32_e32 v129, v221, v129, vcc
	v_cmp_gt_u32_e32 vcc, s75, v212
	s_and_b64 s[30:31], s[92:93], s[30:31]
	s_and_b64 vcc, s[30:31], vcc
	v_add_u32_e32 v212, 0xdf, v204
	v_cndmask_b32_e32 v98, v221, v98, vcc
	v_cmp_gt_u32_e32 vcc, s75, v212
	s_and_b64 s[28:29], s[92:93], s[28:29]
	s_and_b64 vcc, s[28:29], vcc
	v_add_u32_e32 v212, 0xde, v204
	v_cndmask_b32_e32 v99, v221, v99, vcc
	v_cmp_gt_u32_e32 vcc, s75, v212
	s_and_b64 s[26:27], s[92:93], s[26:27]
	s_and_b64 vcc, s[26:27], vcc
	v_add_u32_e32 v212, 0xdd, v204
	v_cndmask_b32_e32 v100, v221, v100, vcc
	v_cmp_gt_u32_e32 vcc, s75, v212
	s_and_b64 s[24:25], s[92:93], s[24:25]
	s_and_b64 vcc, s[24:25], vcc
	v_add_u32_e32 v212, 0xd8, v204
	v_cndmask_b32_e32 v101, v221, v101, vcc
	v_cmp_gt_u32_e32 vcc, s75, v212
	s_and_b64 s[22:23], s[92:93], s[22:23]
	s_and_b64 vcc, s[22:23], vcc
	v_add_u32_e32 v212, 0xd7, v204
	v_cndmask_b32_e32 v102, v221, v102, vcc
	v_cmp_gt_u32_e32 vcc, s75, v212
	s_and_b64 s[20:21], s[92:93], s[20:21]
	s_and_b64 vcc, s[20:21], vcc
	v_add_u32_e32 v212, 0xd6, v204
	v_cndmask_b32_e32 v103, v221, v103, vcc
	v_cmp_gt_u32_e32 vcc, s75, v212
	s_and_b64 s[18:19], s[92:93], s[18:19]
	s_and_b64 vcc, s[18:19], vcc
	v_add_u32_e32 v212, 0xd5, v204
	v_cndmask_b32_e32 v104, v221, v104, vcc
	v_cmp_gt_u32_e32 vcc, s75, v212
	s_and_b64 s[16:17], s[92:93], s[16:17]
	s_and_b64 vcc, s[16:17], vcc
	v_add_u32_e32 v212, 0xd0, v204
	v_cndmask_b32_e32 v105, v221, v105, vcc
	v_cmp_gt_u32_e32 vcc, s75, v212
	s_and_b64 s[14:15], s[92:93], s[14:15]
	s_mov_b32 s62, 0xf149f2ca
	s_and_b64 vcc, s[14:15], vcc
	v_add_u32_e32 v212, 0xcf, v204
	v_max3_f32 v201, v114, s62, v115
	v_cndmask_b32_e32 v106, v221, v106, vcc
	v_cmp_gt_u32_e32 vcc, s75, v212
	s_and_b64 s[12:13], s[92:93], s[12:13]
	v_max3_f32 v201, v201, v116, v117
	s_and_b64 vcc, s[12:13], vcc
	v_add_u32_e32 v212, 0xce, v204
	v_max3_f32 v201, v201, v118, v119
	v_cndmask_b32_e32 v107, v221, v107, vcc
	v_cmp_gt_u32_e32 vcc, s75, v212
	s_and_b64 s[10:11], s[92:93], s[10:11]
	v_max3_f32 v201, v201, v120, v121
	s_and_b64 vcc, s[10:11], vcc
	v_add_u32_e32 v212, 0xcd, v204
	v_max3_f32 v201, v201, v122, v123
	v_cndmask_b32_e32 v108, v221, v108, vcc
	v_cmp_gt_u32_e32 vcc, s75, v212
	s_and_b64 s[8:9], s[92:93], s[8:9]
	v_max3_f32 v201, v201, v124, v125
	s_and_b64 vcc, s[8:9], vcc
	v_add_u32_e32 v212, 0xc8, v204
	v_max3_f32 v201, v201, v126, v127
	v_cndmask_b32_e32 v109, v221, v109, vcc
	v_cmp_gt_u32_e32 vcc, s75, v212
	s_and_b64 s[6:7], s[92:93], s[6:7]
	v_max3_f32 v201, v201, v128, v129
	s_and_b64 vcc, s[6:7], vcc
	v_add_u32_e32 v212, 0xc7, v204
	v_max3_f32 v201, v201, v98, v99
	v_cndmask_b32_e32 v110, v221, v110, vcc
	v_cmp_gt_u32_e32 vcc, s75, v212
	s_and_b64 s[4:5], s[92:93], s[4:5]
	v_max3_f32 v201, v201, v100, v101
	s_and_b64 vcc, s[4:5], vcc
	v_add_u32_e32 v212, 0xc6, v204
	v_max3_f32 v201, v201, v102, v103
	v_cndmask_b32_e32 v111, v221, v111, vcc
	v_cmp_gt_u32_e32 vcc, s75, v212
	s_and_b64 s[4:5], s[92:93], s[66:67]
	v_max3_f32 v201, v201, v104, v105
	s_and_b64 vcc, s[4:5], vcc
	v_add_u32_e32 v212, 0xc5, v204
	v_max3_f32 v201, v201, v106, v107
	v_cndmask_b32_e32 v112, v221, v112, vcc
	v_cmp_gt_u32_e32 vcc, s75, v212
	s_and_b64 s[0:1], s[92:93], s[0:1]
	v_max3_f32 v201, v201, v108, v109
	s_and_b64 vcc, s[0:1], vcc
	v_max3_f32 v201, v201, v110, v111
	v_cndmask_b32_e32 v113, v221, v113, vcc
	v_max3_f32 v201, v201, v112, v113

.LBB0_1043:
	v_add_u32_e32 v3, s5, v1
	v_ashrrev_i32_e32 v10, 5, v3
	v_mad_u64_u32 v[6:7], s[6:7], v10, s3, v[2:3]
	ds_read_b128 v[146:149], v6
	ds_read_b128 v[150:153], v6 offset:8448
	ds_read_b128 v[154:157], v6 offset:16896
	ds_read_b128 v[158:161], v6 offset:25344
	v_add_u32_e32 v10, s4, v10
	v_mad_i64_i32 v[162:163], s[6:7], v10, s68, v[4:5]
	v_add_u32_e32 v11, 16, v10
	v_mad_i64_i32 v[164:165], s[6:7], v11, s68, v[4:5]
	v_add_u32_e32 v11, 32, v10
	v_mad_i64_i32 v[166:167], s[6:7], v11, s68, v[4:5]
	v_add_u32_e32 v11, 48, v10
	v_mad_i64_i32 v[168:169], s[6:7], v11, s68, v[4:5]
	s_addk_i32 s5, 0x800
	s_cmpk_lg_i32 s5, 0x2000
	s_waitcnt lgkmcnt(3)
	global_store_dwordx4 v[162:163], v[146:149], off
	s_waitcnt lgkmcnt(2)
	global_store_dwordx4 v[164:165], v[150:153], off
	s_waitcnt lgkmcnt(1)
	global_store_dwordx4 v[166:167], v[154:157], off
	s_waitcnt lgkmcnt(0)
	global_store_dwordx4 v[168:169], v[158:161], off
	s_cbranch_scc1 .LBB0_1043
	s_add_i32 s20, s20, s74
	s_cmpk_lt_i32 s20, 0xc00
	s_cbranch_scc1 .LBB0_837
	s_branch .LBB0_1046

.LBB0_1111:
	ds_read_b128 v[108:111], v104
	ds_read_b128 v[112:115], v102
	ds_read_b128 v[116:119], v102 offset:4608
	ds_read_b128 v[212:215], v104 offset:8704
	s_waitcnt lgkmcnt(2)
	v_mfma_f32_32x32x16_bf16 v[50:65], v[108:111], v[112:115], v[50:65]
	s_waitcnt lgkmcnt(1)
	v_mfma_f32_32x32x16_bf16 v[34:49], v[108:111], v[116:119], v[34:49]
	ds_read_b128 v[108:111], v104 offset:32
	ds_read_b128 v[216:219], v102 offset:32
	s_waitcnt lgkmcnt(2)
	v_mfma_f32_32x32x16_bf16 v[18:33], v[212:215], v[112:115], v[18:33]
	v_mfma_f32_32x32x16_bf16 v[2:17], v[212:215], v[116:119], v[2:17]
	ds_read_b128 v[116:119], v102 offset:4640
	ds_read_b128 v[212:215], v104 offset:8736
	s_waitcnt lgkmcnt(2)
	v_mfma_f32_32x32x16_bf16 v[50:65], v[108:111], v[216:219], v[50:65]
	s_waitcnt lgkmcnt(1)
	v_mfma_f32_32x32x16_bf16 v[34:49], v[108:111], v[116:119], v[34:49]
	ds_read_b128 v[108:111], v104 offset:64
	ds_read_b128 v[112:115], v102 offset:64
	s_waitcnt lgkmcnt(2)
	v_mfma_f32_32x32x16_bf16 v[18:33], v[212:215], v[216:219], v[18:33]
	v_mfma_f32_32x32x16_bf16 v[2:17], v[212:215], v[116:119], v[2:17]
	ds_read_b128 v[116:119], v102 offset:4672
	ds_read_b128 v[212:215], v104 offset:8768
	s_waitcnt lgkmcnt(2)
	v_mfma_f32_32x32x16_bf16 v[50:65], v[108:111], v[112:115], v[50:65]
	s_waitcnt lgkmcnt(1)
	v_mfma_f32_32x32x16_bf16 v[34:49], v[108:111], v[116:119], v[34:49]
	ds_read_b128 v[108:111], v104 offset:96
	ds_read_b128 v[216:219], v102 offset:96
	s_waitcnt lgkmcnt(2)
	v_mfma_f32_32x32x16_bf16 v[18:33], v[212:215], v[112:115], v[18:33]
	v_mfma_f32_32x32x16_bf16 v[2:17], v[212:215], v[116:119], v[2:17]
	ds_read_b128 v[116:119], v102 offset:4704
	ds_read_b128 v[212:215], v104 offset:8800
	s_waitcnt lgkmcnt(2)
	v_mfma_f32_32x32x16_bf16 v[50:65], v[108:111], v[216:219], v[50:65]
	s_waitcnt lgkmcnt(1)
	v_mfma_f32_32x32x16_bf16 v[34:49], v[108:111], v[116:119], v[34:49]
	s_waitcnt lgkmcnt(0)
	v_mfma_f32_32x32x16_bf16 v[18:33], v[212:215], v[216:219], v[18:33]
	v_mfma_f32_32x32x16_bf16 v[2:17], v[212:215], v[116:119], v[2:17]
	v_add_u32_e32 v104, 64, v101
	v_sub_u32_e32 v101, 63, v101
	v_cndmask_b32_e32 v101, v104, v101, vcc
	v_cvt_f32_i32_e32 v101, v101
	s_waitcnt vmcnt(0)
	v_and_b32_e32 v104, 0xffff0000, v78
	s_barrier
	v_mul_f32_e32 v100, v100, v101
	v_exp_f32_e32 v100, v100
	v_lshlrev_b32_e32 v101, 16, v78
	s_cmp_eq_u32 s16, 15
	v_mul_f32_e32 v101, v100, v101
	v_cvt_pk_bf16_f32 v101, v101, s0
	ds_write_b16 v103, v101
	v_mul_f32_e32 v101, v100, v104
	v_cvt_pk_bf16_f32 v101, v101, s0
	ds_write_b16 v103, v101 offset:144
	v_lshlrev_b32_e32 v101, 16, v79
	v_mul_f32_e32 v101, v100, v101
	v_cvt_pk_bf16_f32 v101, v101, s0
	ds_write_b16 v103, v101 offset:288
	v_and_b32_e32 v101, 0xffff0000, v79
	v_mul_f32_e32 v101, v100, v101
	v_cvt_pk_bf16_f32 v101, v101, s0
	ds_write_b16 v103, v101 offset:432
	v_lshlrev_b32_e32 v101, 16, v80
	v_mul_f32_e32 v101, v100, v101
	v_cvt_pk_bf16_f32 v101, v101, s0
	ds_write_b16 v103, v101 offset:576
	v_and_b32_e32 v101, 0xffff0000, v80
	v_mul_f32_e32 v101, v100, v101
	v_cvt_pk_bf16_f32 v101, v101, s0
	ds_write_b16 v103, v101 offset:720
	v_lshlrev_b32_e32 v101, 16, v81
	v_mul_f32_e32 v101, v100, v101
	v_cvt_pk_bf16_f32 v101, v101, s0
	ds_write_b16 v103, v101 offset:864
	v_and_b32_e32 v101, 0xffff0000, v81
	v_mul_f32_e32 v101, v100, v101
	v_cvt_pk_bf16_f32 v101, v101, s0
	ds_write_b16 v103, v101 offset:1008
	v_lshlrev_b32_e32 v101, 16, v74
	v_mul_f32_e32 v101, v100, v101
	v_cvt_pk_bf16_f32 v101, v101, s0
	ds_write_b16 v103, v101 offset:1152
	v_and_b32_e32 v101, 0xffff0000, v74
	v_mul_f32_e32 v101, v100, v101
	v_cvt_pk_bf16_f32 v101, v101, s0
	ds_write_b16 v103, v101 offset:1296
	v_lshlrev_b32_e32 v101, 16, v75
	v_mul_f32_e32 v101, v100, v101
	v_cvt_pk_bf16_f32 v101, v101, s0
	ds_write_b16 v103, v101 offset:1440
	v_and_b32_e32 v101, 0xffff0000, v75
	v_mul_f32_e32 v101, v100, v101
	v_cvt_pk_bf16_f32 v101, v101, s0
	ds_write_b16 v103, v101 offset:1584
	v_lshlrev_b32_e32 v101, 16, v76
	v_mul_f32_e32 v101, v100, v101
	v_cvt_pk_bf16_f32 v101, v101, s0
	ds_write_b16 v103, v101 offset:1728
	v_and_b32_e32 v101, 0xffff0000, v76
	v_mul_f32_e32 v101, v100, v101
	v_cvt_pk_bf16_f32 v101, v101, s0
	ds_write_b16 v103, v101 offset:1872
	v_lshlrev_b32_e32 v101, 16, v77
	v_mul_f32_e32 v101, v100, v101
	v_cvt_pk_bf16_f32 v101, v101, s0
	ds_write_b16 v103, v101 offset:2016
	v_and_b32_e32 v101, 0xffff0000, v77
	v_mul_f32_e32 v101, v100, v101
	v_cvt_pk_bf16_f32 v101, v101, s0
	ds_write_b16 v103, v101 offset:2160
	v_lshlrev_b32_e32 v101, 16, v70
	v_mul_f32_e32 v101, v100, v101
	v_cvt_pk_bf16_f32 v101, v101, s0
	ds_write_b16 v103, v101 offset:2304
	v_and_b32_e32 v101, 0xffff0000, v70
	v_mul_f32_e32 v101, v100, v101
	v_cvt_pk_bf16_f32 v101, v101, s0
	ds_write_b16 v103, v101 offset:2448
	v_lshlrev_b32_e32 v101, 16, v71
	v_mul_f32_e32 v101, v100, v101
	v_cvt_pk_bf16_f32 v101, v101, s0
	ds_write_b16 v103, v101 offset:2592
	v_and_b32_e32 v101, 0xffff0000, v71
	v_mul_f32_e32 v101, v100, v101
	v_cvt_pk_bf16_f32 v101, v101, s0
	ds_write_b16 v103, v101 offset:2736
	v_lshlrev_b32_e32 v101, 16, v72
	v_mul_f32_e32 v101, v100, v101
	v_cvt_pk_bf16_f32 v101, v101, s0
	ds_write_b16 v103, v101 offset:2880
	v_and_b32_e32 v101, 0xffff0000, v72
	v_mul_f32_e32 v101, v100, v101
	v_cvt_pk_bf16_f32 v101, v101, s0
	ds_write_b16 v103, v101 offset:3024
	v_lshlrev_b32_e32 v101, 16, v73
	v_mul_f32_e32 v101, v100, v101
	v_cvt_pk_bf16_f32 v101, v101, s0
	ds_write_b16 v103, v101 offset:3168
	v_and_b32_e32 v101, 0xffff0000, v73
	v_mul_f32_e32 v101, v100, v101
	v_cvt_pk_bf16_f32 v101, v101, s0
	ds_write_b16 v103, v101 offset:3312
	v_lshlrev_b32_e32 v101, 16, v66
	v_mul_f32_e32 v101, v100, v101
	v_cvt_pk_bf16_f32 v101, v101, s0
	ds_write_b16 v103, v101 offset:3456
	v_and_b32_e32 v101, 0xffff0000, v66
	v_mul_f32_e32 v101, v100, v101
	v_cvt_pk_bf16_f32 v101, v101, s0
	ds_write_b16 v103, v101 offset:3600
	v_lshlrev_b32_e32 v101, 16, v67
	v_mul_f32_e32 v101, v100, v101
	v_cvt_pk_bf16_f32 v101, v101, s0
	ds_write_b16 v103, v101 offset:3744
	v_and_b32_e32 v101, 0xffff0000, v67
	v_mul_f32_e32 v101, v100, v101
	v_cvt_pk_bf16_f32 v101, v101, s0
	ds_write_b16 v103, v101 offset:3888
	v_lshlrev_b32_e32 v101, 16, v68
	v_mul_f32_e32 v101, v100, v101
	v_cvt_pk_bf16_f32 v101, v101, s0
	ds_write_b16 v103, v101 offset:4032
	v_and_b32_e32 v101, 0xffff0000, v68
	v_mul_f32_e32 v101, v100, v101
	v_cvt_pk_bf16_f32 v101, v101, s0
	ds_write_b16 v103, v101 offset:4176
	v_lshlrev_b32_e32 v101, 16, v69
	v_mul_f32_e32 v101, v100, v101
	v_cvt_pk_bf16_f32 v101, v101, s0
	ds_write_b16 v103, v101 offset:4320
	v_and_b32_e32 v101, 0xffff0000, v69
	v_mul_f32_e32 v100, v100, v101
	v_cvt_pk_bf16_f32 v100, v100, s0
	ds_write_b16 v103, v100 offset:4464
	s_cbranch_scc1 .LBB0_1114
	s_add_i32 s0, s0, s17
	s_lshl_b32 s0, s0, 7
	s_ashr_i32 s1, s0, 31
	v_lshl_add_u64 v[66:67], v[90:91], 0, s[0:1]
	v_mov_b64_e32 v[68:69], s[8:9]
	v_mad_u64_u32 v[68:69], s[0:1], v66, s68, v[68:69]
	v_mov_b32_e32 v66, v69
	v_mad_u64_u32 v[66:67], s[0:1], v67, s68, v[66:67]
	v_mov_b32_e32 v69, v66
	v_lshl_add_u64 v[66:67], v[68:69], 0, s[72:73]
	s_mov_b32 s11, s73
	v_lshl_add_u64 v[66:67], v[66:67], 0, s[10:11]
	v_lshl_add_u64 v[66:67], v[86:87], 1, v[66:67]
	v_lshl_add_u64 v[74:75], v[66:67], 0, s[82:83]
	v_add_co_u32_e64 v66, s[0:1], s94, v66
	s_nop 1
	v_addc_co_u32_e64 v67, s[0:1], 0, v67, s[0:1]
	global_load_dwordx4 v[78:81], v[66:67], off
	s_nop 0
	global_load_dwordx4 v[66:69], v[74:75], off offset:48
	global_load_dwordx4 v[70:73], v[74:75], off offset:32
	s_nop 0
	global_load_dwordx4 v[74:77], v[74:75], off offset:16

.LBB0_1115:
	ds_read_b128 v[104:107], v99
	ds_read_b128 v[108:111], v102
	ds_read_b128 v[112:115], v102 offset:4608
	ds_read_b128 v[212:215], v99 offset:8704
	s_waitcnt lgkmcnt(2)
	v_mfma_f32_32x32x16_bf16 v[50:65], v[104:107], v[108:111], v[50:65]
	s_waitcnt lgkmcnt(1)
	v_mfma_f32_32x32x16_bf16 v[34:49], v[104:107], v[112:115], v[34:49]
	ds_read_b128 v[104:107], v99 offset:32
	ds_read_b128 v[216:219], v102 offset:32
	s_waitcnt lgkmcnt(2)
	v_mfma_f32_32x32x16_bf16 v[18:33], v[212:215], v[108:111], v[18:33]
	v_mfma_f32_32x32x16_bf16 v[2:17], v[212:215], v[112:115], v[2:17]
	ds_read_b128 v[112:115], v102 offset:4640
	ds_read_b128 v[212:215], v99 offset:8736
	s_waitcnt lgkmcnt(2)
	v_mfma_f32_32x32x16_bf16 v[50:65], v[104:107], v[216:219], v[50:65]
	s_waitcnt lgkmcnt(1)
	v_mfma_f32_32x32x16_bf16 v[34:49], v[104:107], v[112:115], v[34:49]
	ds_read_b128 v[104:107], v99 offset:64
	ds_read_b128 v[108:111], v102 offset:64
	s_waitcnt lgkmcnt(2)
	v_mfma_f32_32x32x16_bf16 v[18:33], v[212:215], v[216:219], v[18:33]
	v_mfma_f32_32x32x16_bf16 v[2:17], v[212:215], v[112:115], v[2:17]
	ds_read_b128 v[112:115], v102 offset:4672
	ds_read_b128 v[212:215], v99 offset:8768
	s_waitcnt lgkmcnt(2)
	v_mfma_f32_32x32x16_bf16 v[50:65], v[104:107], v[108:111], v[50:65]
	s_waitcnt lgkmcnt(1)
	v_mfma_f32_32x32x16_bf16 v[34:49], v[104:107], v[112:115], v[34:49]
	ds_read_b128 v[104:107], v99 offset:96
	ds_read_b128 v[216:219], v102 offset:96
	s_waitcnt lgkmcnt(2)
	v_mfma_f32_32x32x16_bf16 v[18:33], v[212:215], v[108:111], v[18:33]
	v_mfma_f32_32x32x16_bf16 v[2:17], v[212:215], v[112:115], v[2:17]
	ds_read_b128 v[112:115], v102 offset:4704
	ds_read_b128 v[212:215], v99 offset:8800
	s_waitcnt lgkmcnt(2)
	v_mfma_f32_32x32x16_bf16 v[50:65], v[104:107], v[216:219], v[50:65]
	s_waitcnt lgkmcnt(1)
	v_mfma_f32_32x32x16_bf16 v[34:49], v[104:107], v[112:115], v[34:49]
	s_waitcnt lgkmcnt(0)
	v_mfma_f32_32x32x16_bf16 v[18:33], v[212:215], v[216:219], v[18:33]
	v_mfma_f32_32x32x16_bf16 v[2:17], v[212:215], v[112:115], v[2:17]
	s_add_i32 s16, s16, 1
	s_cmp_lg_u32 s16, 16
	s_cbranch_scc1 .LBB0_1110
	v_readlane_b32 s8, v254, 37
	v_readlane_b32 s10, v254, 39
	v_readlane_b32 s9, v254, 38
	v_readlane_b32 s11, v254, 40
	s_add_u32 s4, s10, s4
	s_addc_u32 s5, s11, s5
	s_lshl_b32 s9, s7, 17
	s_ashr_i32 s7, s6, 31
	s_lshl_b32 s8, s13, 1
	s_lshl_b64 s[0:1], s[6:7], 3
	s_or_b32 s0, s0, s8
	s_or_b32 s0, s0, s14
	s_lshl_b64 s[0:1], s[0:1], 19
	s_add_u32 s0, s4, s0
	s_addc_u32 s1, s5, s1
	v_ashrrev_i32_e32 v83, 31, v82
	s_add_u32 s0, s0, s9
	s_waitcnt vmcnt(2)
	v_lshlrev_b64 v[66:67], 8, v[82:83]
	s_addc_u32 s1, s1, 0
	v_lshl_add_u64 v[66:67], s[0:1], 0, v[66:67]
	s_mov_b64 s[0:1], 0x9981000
	v_lshl_add_u64 v[68:69], v[66:67], 0, s[0:1]
	s_mov_b32 s0, 0x9981000
	v_add_co_u32_e32 v66, vcc, s0, v66
	s_add_i32 s12, s12, s74
	s_nop 0
	v_addc_co_u32_e32 v67, vcc, 0, v67, vcc
	s_cmpk_lt_i32 s12, 0x200
	global_store_dwordx4 v[66:67], v[50:53], off
	global_store_dwordx4 v[68:69], v[54:57], off offset:16
	global_store_dwordx4 v[68:69], v[58:61], off offset:32
	global_store_dwordx4 v[68:69], v[62:65], off offset:48
	global_store_dwordx4 v[68:69], v[34:37], off offset:64
	global_store_dwordx4 v[68:69], v[38:41], off offset:80
	global_store_dwordx4 v[68:69], v[42:45], off offset:96
	global_store_dwordx4 v[68:69], v[46:49], off offset:112
	global_store_dwordx4 v[68:69], v[18:21], off offset:128
	global_store_dwordx4 v[68:69], v[22:25], off offset:144
	global_store_dwordx4 v[68:69], v[26:29], off offset:160
	global_store_dwordx4 v[68:69], v[30:33], off offset:176
	global_store_dwordx4 v[68:69], v[2:5], off offset:192
	global_store_dwordx4 v[68:69], v[6:9], off offset:208
	global_store_dwordx4 v[68:69], v[10:13], off offset:224
	global_store_dwordx4 v[68:69], v[14:17], off offset:240
	s_barrier
	s_cbranch_scc1 .LBB0_1101

.LBB0_1207:
	ds_read_b128 v[2:5], v196
	ds_read_b128 v[6:9], v203
	ds_read_b128 v[216:219], v203 offset:4608
	ds_read_b128 v[212:215], v196 offset:32
	s_waitcnt lgkmcnt(2)
	v_mfma_f32_32x32x16_bf16 v[128:143], v[2:5], v[6:9], v[128:143]
	ds_read_b128 v[6:9], v203 offset:32
	s_waitcnt lgkmcnt(2)
	v_mfma_f32_32x32x16_bf16 v[112:127], v[2:5], v[216:219], v[112:127]
	ds_read_b128 v[216:219], v203 offset:4640
	ds_read_b128 v[2:5], v196 offset:64
	s_waitcnt lgkmcnt(2)
	v_mfma_f32_32x32x16_bf16 v[128:143], v[212:215], v[6:9], v[128:143]
	ds_read_b128 v[6:9], v203 offset:64
	s_waitcnt lgkmcnt(2)
	v_mfma_f32_32x32x16_bf16 v[112:127], v[212:215], v[216:219], v[112:127]
	ds_read_b128 v[216:219], v203 offset:4672
	ds_read_b128 v[212:215], v196 offset:96
	s_waitcnt lgkmcnt(2)
	v_mfma_f32_32x32x16_bf16 v[128:143], v[2:5], v[6:9], v[128:143]
	ds_read_b128 v[6:9], v203 offset:96
	s_waitcnt lgkmcnt(2)
	v_mfma_f32_32x32x16_bf16 v[112:127], v[2:5], v[216:219], v[112:127]
	ds_read_b128 v[216:219], v203 offset:4704
	s_waitcnt lgkmcnt(1)
	v_mfma_f32_32x32x16_bf16 v[128:143], v[212:215], v[6:9], v[128:143]
	s_waitcnt lgkmcnt(0)
	v_mfma_f32_32x32x16_bf16 v[112:127], v[212:215], v[216:219], v[112:127]

.LBB0_1209:
	ds_read_b128 v[2:5], v196
	ds_read_b128 v[6:9], v202
	ds_read_b128 v[216:219], v202 offset:16896
	ds_read_b128 v[212:215], v196 offset:32
	s_waitcnt lgkmcnt(2)
	v_mfma_f32_32x32x16_bf16 v[96:111], v[2:5], v[6:9], v[96:111]
	ds_read_b128 v[6:9], v202 offset:32
	s_waitcnt lgkmcnt(2)
	v_mfma_f32_32x32x16_bf16 v[80:95], v[2:5], v[216:219], v[80:95]
	ds_read_b128 v[216:219], v202 offset:16928
	ds_read_b128 v[2:5], v196 offset:64
	s_waitcnt lgkmcnt(2)
	v_mfma_f32_32x32x16_bf16 v[96:111], v[212:215], v[6:9], v[96:111]
	ds_read_b128 v[6:9], v202 offset:64
	s_waitcnt lgkmcnt(2)
	v_mfma_f32_32x32x16_bf16 v[80:95], v[212:215], v[216:219], v[80:95]
	ds_read_b128 v[216:219], v202 offset:16960
	ds_read_b128 v[212:215], v196 offset:96
	s_waitcnt lgkmcnt(2)
	v_mfma_f32_32x32x16_bf16 v[96:111], v[2:5], v[6:9], v[96:111]
	ds_read_b128 v[6:9], v202 offset:96
	s_waitcnt lgkmcnt(2)
	v_mfma_f32_32x32x16_bf16 v[80:95], v[2:5], v[216:219], v[80:95]
	ds_read_b128 v[216:219], v202 offset:16992
	s_waitcnt lgkmcnt(1)
	v_mfma_f32_32x32x16_bf16 v[96:111], v[212:215], v[6:9], v[96:111]
	s_waitcnt lgkmcnt(0)
	v_mfma_f32_32x32x16_bf16 v[80:95], v[212:215], v[216:219], v[80:95]
	s_add_i32 s13, s13, 1
	s_cmp_lg_u32 s13, 4
	v_add_u32_e32 v202, 0x80, v202
	s_cbranch_scc1 .LBB0_1195
	v_cndmask_b32_e64 v1, 0, 1, s[18:19]
	v_ashrrev_i32_e32 v3, 3, v244
	s_mov_b64 s[22:23], -1
	v_cmp_ne_u32_e64 s[0:1], 1, v1
	s_andn2_b64 vcc, exec, s[18:19]
	v_and_b32_e32 v2, -4, v3
	s_barrier
	s_cbranch_vccnz .LBB0_1213
	v_and_b32_e32 v1, -4, v3
	v_add_u32_e32 v14, v1, v226
	v_or_b32_e32 v180, 1, v14
	v_or_b32_e32 v182, 2, v14
	v_or_b32_e32 v184, 3, v14
	v_add_u32_e32 v186, 8, v14
	v_add_u32_e32 v188, 9, v14
	v_add_u32_e32 v190, 10, v14
	v_add_u32_e32 v192, 11, v14
	v_add_u32_e32 v194, 16, v14
	v_add_u32_e32 v196, 17, v14
	v_add_u32_e32 v198, 18, v14
	v_add_u32_e32 v200, 19, v14
	v_add_u32_e32 v202, 24, v14
	v_add_u32_e32 v204, 25, v14
	v_add_u32_e32 v206, 26, v14
	v_add_u32_e32 v208, 27, v14
	s_mov_b64 s[22:23], 0

.LBB0_1219:
	ds_read_b128 v[118:121], v15
	ds_read_b128 v[122:125], v117
	ds_read_b128 v[216:219], v117 offset:8704
	ds_read_b128 v[212:215], v15 offset:32
	s_waitcnt lgkmcnt(2)
	v_mfma_f32_32x32x16_bf16 v[96:111], v[118:121], v[122:125], v[96:111]
	ds_read_b128 v[122:125], v117 offset:32
	s_waitcnt lgkmcnt(2)
	v_mfma_f32_32x32x16_bf16 v[80:95], v[118:121], v[216:219], v[80:95]
	ds_read_b128 v[216:219], v117 offset:8736
	ds_read_b128 v[118:121], v15 offset:64
	s_waitcnt lgkmcnt(2)
	v_mfma_f32_32x32x16_bf16 v[96:111], v[212:215], v[122:125], v[96:111]
	ds_read_b128 v[122:125], v117 offset:64
	s_waitcnt lgkmcnt(2)
	v_mfma_f32_32x32x16_bf16 v[80:95], v[212:215], v[216:219], v[80:95]
	ds_read_b128 v[216:219], v117 offset:8768
	ds_read_b128 v[212:215], v15 offset:96
	s_waitcnt lgkmcnt(2)
	v_mfma_f32_32x32x16_bf16 v[96:111], v[118:121], v[122:125], v[96:111]
	ds_read_b128 v[122:125], v117 offset:96
	s_waitcnt lgkmcnt(2)
	v_mfma_f32_32x32x16_bf16 v[80:95], v[118:121], v[216:219], v[80:95]
	ds_read_b128 v[216:219], v117 offset:8800
	ds_read_b128 v[118:121], v15 offset:128
	s_waitcnt lgkmcnt(2)
	v_mfma_f32_32x32x16_bf16 v[96:111], v[212:215], v[122:125], v[96:111]
	ds_read_b128 v[122:125], v117 offset:128
	s_waitcnt lgkmcnt(2)
	v_mfma_f32_32x32x16_bf16 v[80:95], v[212:215], v[216:219], v[80:95]
	ds_read_b128 v[216:219], v117 offset:8832
	ds_read_b128 v[212:215], v15 offset:160
	s_waitcnt lgkmcnt(2)
	v_mfma_f32_32x32x16_bf16 v[96:111], v[118:121], v[122:125], v[96:111]
	ds_read_b128 v[122:125], v117 offset:160
	s_waitcnt lgkmcnt(2)
	v_mfma_f32_32x32x16_bf16 v[80:95], v[118:121], v[216:219], v[80:95]
	ds_read_b128 v[216:219], v117 offset:8864
	ds_read_b128 v[118:121], v15 offset:192
	s_waitcnt lgkmcnt(2)
	v_mfma_f32_32x32x16_bf16 v[96:111], v[212:215], v[122:125], v[96:111]
	ds_read_b128 v[122:125], v117 offset:192
	s_waitcnt lgkmcnt(2)
	v_mfma_f32_32x32x16_bf16 v[80:95], v[212:215], v[216:219], v[80:95]
	ds_read_b128 v[216:219], v117 offset:8896
	ds_read_b128 v[212:215], v15 offset:224
	s_waitcnt lgkmcnt(2)
	v_mfma_f32_32x32x16_bf16 v[96:111], v[118:121], v[122:125], v[96:111]
	ds_read_b128 v[122:125], v117 offset:224
	s_waitcnt lgkmcnt(2)
	v_mfma_f32_32x32x16_bf16 v[80:95], v[118:121], v[216:219], v[80:95]
	ds_read_b128 v[216:219], v117 offset:8928
	s_waitcnt lgkmcnt(1)
	v_mfma_f32_32x32x16_bf16 v[96:111], v[212:215], v[122:125], v[96:111]
	s_waitcnt lgkmcnt(0)
	v_mfma_f32_32x32x16_bf16 v[80:95], v[212:215], v[216:219], v[80:95]
	s_mov_b64 s[0:1], s[6:7]
	s_branch .LBB0_1222

.LBB0_1223:
	ds_read_b128 v[10:13], v3
	ds_read_b128 v[80:83], v7
	ds_read_b128 v[84:87], v6
	ds_read_b128 v[212:215], v2
	s_waitcnt lgkmcnt(2)
	v_mfma_f32_32x32x16_bf16 v[64:79], v[10:13], v[80:83], v[64:79]
	s_waitcnt lgkmcnt(1)
	v_mfma_f32_32x32x16_bf16 v[48:63], v[10:13], v[84:87], v[48:63]
	ds_read_b128 v[10:13], v3 offset:32
	ds_read_b128 v[216:219], v7 offset:32
	s_waitcnt lgkmcnt(2)
	v_mfma_f32_32x32x16_bf16 v[32:47], v[212:215], v[80:83], v[32:47]
	v_mfma_f32_32x32x16_bf16 v[16:31], v[212:215], v[84:87], v[16:31]
	ds_read_b128 v[84:87], v6 offset:32
	ds_read_b128 v[212:215], v2 offset:32
	s_waitcnt lgkmcnt(2)
	v_mfma_f32_32x32x16_bf16 v[64:79], v[10:13], v[216:219], v[64:79]
	s_waitcnt lgkmcnt(1)
	v_mfma_f32_32x32x16_bf16 v[48:63], v[10:13], v[84:87], v[48:63]
	ds_read_b128 v[10:13], v3 offset:64
	ds_read_b128 v[80:83], v7 offset:64
	s_waitcnt lgkmcnt(2)
	v_mfma_f32_32x32x16_bf16 v[32:47], v[212:215], v[216:219], v[32:47]
	v_mfma_f32_32x32x16_bf16 v[16:31], v[212:215], v[84:87], v[16:31]
	ds_read_b128 v[84:87], v6 offset:64
	ds_read_b128 v[212:215], v2 offset:64
	s_waitcnt lgkmcnt(2)
	v_mfma_f32_32x32x16_bf16 v[64:79], v[10:13], v[80:83], v[64:79]
	s_waitcnt lgkmcnt(1)
	v_mfma_f32_32x32x16_bf16 v[48:63], v[10:13], v[84:87], v[48:63]
	ds_read_b128 v[10:13], v3 offset:96
	ds_read_b128 v[216:219], v7 offset:96
	s_waitcnt lgkmcnt(2)
	v_mfma_f32_32x32x16_bf16 v[32:47], v[212:215], v[80:83], v[32:47]
	v_mfma_f32_32x32x16_bf16 v[16:31], v[212:215], v[84:87], v[16:31]
	ds_read_b128 v[84:87], v6 offset:96
	ds_read_b128 v[212:215], v2 offset:96
	s_waitcnt lgkmcnt(2)
	v_mfma_f32_32x32x16_bf16 v[64:79], v[10:13], v[216:219], v[64:79]
	s_waitcnt lgkmcnt(1)
	v_mfma_f32_32x32x16_bf16 v[48:63], v[10:13], v[84:87], v[48:63]
	s_waitcnt lgkmcnt(0)
	v_mfma_f32_32x32x16_bf16 v[32:47], v[212:215], v[216:219], v[32:47]
	v_mfma_f32_32x32x16_bf16 v[16:31], v[212:215], v[84:87], v[16:31]
	v_add_u32_e32 v2, 64, v244
	v_sub_u32_e32 v3, 63, v244
	v_cndmask_b32_e64 v2, v2, v3, s[16:17]
	v_cvt_f32_i32_e32 v2, v2
	s_waitcnt vmcnt(0)
	v_lshlrev_b32_e32 v3, 16, v152
	v_and_b32_e32 v4, 0xffff0000, v152
	v_mul_f32_e32 v2, v243, v2
	v_exp_f32_e32 v2, v2
	s_barrier
	s_cmp_eq_u32 s29, 15
	v_mul_f32_e32 v3, v2, v3
	v_cvt_pk_bf16_f32 v3, v3, s0
	ds_write_b16 v14, v3
	v_mul_f32_e32 v3, v2, v4
	v_cvt_pk_bf16_f32 v3, v3, s0
	ds_write_b16 v14, v3 offset:144
	v_lshlrev_b32_e32 v3, 16, v153
	v_mul_f32_e32 v3, v2, v3
	v_cvt_pk_bf16_f32 v3, v3, s0
	ds_write_b16 v14, v3 offset:288
	v_and_b32_e32 v3, 0xffff0000, v153
	v_mul_f32_e32 v3, v2, v3
	v_cvt_pk_bf16_f32 v3, v3, s0
	ds_write_b16 v14, v3 offset:432
	v_lshlrev_b32_e32 v3, 16, v154
	v_mul_f32_e32 v3, v2, v3
	v_cvt_pk_bf16_f32 v3, v3, s0
	ds_write_b16 v14, v3 offset:576
	v_and_b32_e32 v3, 0xffff0000, v154
	v_mul_f32_e32 v3, v2, v3
	v_cvt_pk_bf16_f32 v3, v3, s0
	ds_write_b16 v14, v3 offset:720
	v_lshlrev_b32_e32 v3, 16, v155
	v_mul_f32_e32 v3, v2, v3
	v_cvt_pk_bf16_f32 v3, v3, s0
	ds_write_b16 v14, v3 offset:864
	v_and_b32_e32 v3, 0xffff0000, v155
	v_mul_f32_e32 v3, v2, v3
	v_cvt_pk_bf16_f32 v3, v3, s0
	ds_write_b16 v14, v3 offset:1008
	v_lshlrev_b32_e32 v3, 16, v156
	v_mul_f32_e32 v3, v2, v3
	v_cvt_pk_bf16_f32 v3, v3, s0
	ds_write_b16 v14, v3 offset:1152
	v_and_b32_e32 v3, 0xffff0000, v156
	v_mul_f32_e32 v3, v2, v3
	v_cvt_pk_bf16_f32 v3, v3, s0
	ds_write_b16 v14, v3 offset:1296
	v_lshlrev_b32_e32 v3, 16, v157
	v_mul_f32_e32 v3, v2, v3
	v_cvt_pk_bf16_f32 v3, v3, s0
	ds_write_b16 v14, v3 offset:1440
	v_and_b32_e32 v3, 0xffff0000, v157
	v_mul_f32_e32 v3, v2, v3
	v_cvt_pk_bf16_f32 v3, v3, s0
	ds_write_b16 v14, v3 offset:1584
	v_lshlrev_b32_e32 v3, 16, v158
	v_mul_f32_e32 v3, v2, v3
	v_cvt_pk_bf16_f32 v3, v3, s0
	ds_write_b16 v14, v3 offset:1728
	v_and_b32_e32 v3, 0xffff0000, v158
	v_mul_f32_e32 v3, v2, v3
	v_cvt_pk_bf16_f32 v3, v3, s0
	ds_write_b16 v14, v3 offset:1872
	v_lshlrev_b32_e32 v3, 16, v159
	v_mul_f32_e32 v3, v2, v3
	v_cvt_pk_bf16_f32 v3, v3, s0
	ds_write_b16 v14, v3 offset:2016
	v_and_b32_e32 v3, 0xffff0000, v159
	v_mul_f32_e32 v3, v2, v3
	v_cvt_pk_bf16_f32 v3, v3, s0
	ds_write_b16 v14, v3 offset:2160
	v_lshlrev_b32_e32 v3, 16, v144
	v_mul_f32_e32 v3, v2, v3
	v_cvt_pk_bf16_f32 v3, v3, s0
	ds_write_b16 v14, v3 offset:2304
	v_and_b32_e32 v3, 0xffff0000, v144
	v_mul_f32_e32 v3, v2, v3
	v_cvt_pk_bf16_f32 v3, v3, s0
	ds_write_b16 v14, v3 offset:2448
	v_lshlrev_b32_e32 v3, 16, v145
	v_mul_f32_e32 v3, v2, v3
	v_cvt_pk_bf16_f32 v3, v3, s0
	ds_write_b16 v14, v3 offset:2592
	v_and_b32_e32 v3, 0xffff0000, v145
	v_mul_f32_e32 v3, v2, v3
	v_cvt_pk_bf16_f32 v3, v3, s0
	ds_write_b16 v14, v3 offset:2736
	v_lshlrev_b32_e32 v3, 16, v146
	v_mul_f32_e32 v3, v2, v3
	v_cvt_pk_bf16_f32 v3, v3, s0
	ds_write_b16 v14, v3 offset:2880
	v_and_b32_e32 v3, 0xffff0000, v146
	v_mul_f32_e32 v3, v2, v3
	v_cvt_pk_bf16_f32 v3, v3, s0
	ds_write_b16 v14, v3 offset:3024
	v_lshlrev_b32_e32 v3, 16, v147
	v_mul_f32_e32 v3, v2, v3
	v_cvt_pk_bf16_f32 v3, v3, s0
	ds_write_b16 v14, v3 offset:3168
	v_and_b32_e32 v3, 0xffff0000, v147
	v_mul_f32_e32 v3, v2, v3
	v_cvt_pk_bf16_f32 v3, v3, s0
	ds_write_b16 v14, v3 offset:3312
	v_lshlrev_b32_e32 v3, 16, v148
	v_mul_f32_e32 v3, v2, v3
	v_cvt_pk_bf16_f32 v3, v3, s0
	ds_write_b16 v14, v3 offset:3456
	v_and_b32_e32 v3, 0xffff0000, v148
	v_mul_f32_e32 v3, v2, v3
	v_cvt_pk_bf16_f32 v3, v3, s0
	ds_write_b16 v14, v3 offset:3600
	v_lshlrev_b32_e32 v3, 16, v149
	v_mul_f32_e32 v3, v2, v3
	v_cvt_pk_bf16_f32 v3, v3, s0
	ds_write_b16 v14, v3 offset:3744
	v_and_b32_e32 v3, 0xffff0000, v149
	v_mul_f32_e32 v3, v2, v3
	v_cvt_pk_bf16_f32 v3, v3, s0
	ds_write_b16 v14, v3 offset:3888
	v_lshlrev_b32_e32 v3, 16, v150
	v_mul_f32_e32 v3, v2, v3
	v_cvt_pk_bf16_f32 v3, v3, s0
	ds_write_b16 v14, v3 offset:4032
	v_and_b32_e32 v3, 0xffff0000, v150
	v_mul_f32_e32 v3, v2, v3
	v_cvt_pk_bf16_f32 v3, v3, s0
	ds_write_b16 v14, v3 offset:4176
	v_lshlrev_b32_e32 v3, 16, v151
	v_mul_f32_e32 v3, v2, v3
	v_cvt_pk_bf16_f32 v3, v3, s0
	ds_write_b16 v14, v3 offset:4320
	v_and_b32_e32 v3, 0xffff0000, v151
	v_mul_f32_e32 v2, v2, v3
	v_cvt_pk_bf16_f32 v2, v2, s0
	ds_write_b16 v14, v2 offset:4464
	s_cbranch_scc1 .LBB0_1229
	s_add_i32 s30, s30, s28
	s_lshl_b32 s0, s30, 7
	s_ashr_i32 s1, s0, 31
	s_add_u32 s20, s0, s10
	s_addc_u32 s21, s1, s11
	v_lshl_add_u64 v[4:5], s[20:21], 0, v[168:169]
	v_mad_u64_u32 v[2:3], s[0:1], v4, s68, v[170:171]
	v_mad_i32_i24 v3, v5, s68, v3
	global_load_dwordx4 v[152:155], v[2:3], off
	s_mov_b64 s[0:1], -1
	s_and_b64 vcc, exec, s[18:19]
	v_lshl_add_u64 v[4:5], s[20:21], 0, v[172:173]
	s_cbranch_vccz .LBB0_1227
	v_mad_u64_u32 v[10:11], s[0:1], v4, s68, v[170:171]
	v_mad_i32_i24 v11, v5, s68, v11
	global_load_dwordx4 v[156:159], v[10:11], off
	s_mov_b64 s[0:1], 0

.LBB0_1230:
	ds_read_b128 v[8:11], v3
	ds_read_b128 v[12:15], v7
	ds_read_b128 v[80:83], v6
	ds_read_b128 v[212:215], v2
	s_waitcnt lgkmcnt(2)
	v_mfma_f32_32x32x16_bf16 v[64:79], v[8:11], v[12:15], v[64:79]
	s_waitcnt lgkmcnt(1)
	v_mfma_f32_32x32x16_bf16 v[48:63], v[8:11], v[80:83], v[48:63]
	ds_read_b128 v[8:11], v3 offset:32
	ds_read_b128 v[216:219], v7 offset:32
	s_waitcnt lgkmcnt(2)
	v_mfma_f32_32x32x16_bf16 v[32:47], v[212:215], v[12:15], v[32:47]
	v_mfma_f32_32x32x16_bf16 v[16:31], v[212:215], v[80:83], v[16:31]
	ds_read_b128 v[80:83], v6 offset:32
	ds_read_b128 v[212:215], v2 offset:32
	s_waitcnt lgkmcnt(2)
	v_mfma_f32_32x32x16_bf16 v[64:79], v[8:11], v[216:219], v[64:79]
	s_waitcnt lgkmcnt(1)
	v_mfma_f32_32x32x16_bf16 v[48:63], v[8:11], v[80:83], v[48:63]
	ds_read_b128 v[8:11], v3 offset:64
	ds_read_b128 v[12:15], v7 offset:64
	s_waitcnt lgkmcnt(2)
	v_mfma_f32_32x32x16_bf16 v[32:47], v[212:215], v[216:219], v[32:47]
	v_mfma_f32_32x32x16_bf16 v[16:31], v[212:215], v[80:83], v[16:31]
	ds_read_b128 v[80:83], v6 offset:64
	ds_read_b128 v[212:215], v2 offset:64
	s_waitcnt lgkmcnt(2)
	v_mfma_f32_32x32x16_bf16 v[64:79], v[8:11], v[12:15], v[64:79]
	s_waitcnt lgkmcnt(1)
	v_mfma_f32_32x32x16_bf16 v[48:63], v[8:11], v[80:83], v[48:63]
	ds_read_b128 v[8:11], v3 offset:96
	ds_read_b128 v[216:219], v7 offset:96
	s_waitcnt lgkmcnt(2)
	v_mfma_f32_32x32x16_bf16 v[32:47], v[212:215], v[12:15], v[32:47]
	v_mfma_f32_32x32x16_bf16 v[16:31], v[212:215], v[80:83], v[16:31]
	ds_read_b128 v[80:83], v6 offset:96
	ds_read_b128 v[212:215], v2 offset:96
	s_waitcnt lgkmcnt(2)
	v_mfma_f32_32x32x16_bf16 v[64:79], v[8:11], v[216:219], v[64:79]
	s_waitcnt lgkmcnt(1)
	v_mfma_f32_32x32x16_bf16 v[48:63], v[8:11], v[80:83], v[48:63]
	s_waitcnt lgkmcnt(0)
	v_mfma_f32_32x32x16_bf16 v[32:47], v[212:215], v[216:219], v[32:47]
	v_mfma_f32_32x32x16_bf16 v[16:31], v[212:215], v[80:83], v[16:31]
	v_add_u32_e32 v1, v1, v175
	v_add_u32_e32 v2, v241, v223
	v_lshlrev_b32_e32 v3, 1, v242
	v_mul_lo_u32 v1, v1, s3
	v_add3_u32 v1, v2, v3, v1
	v_cvt_pk_bf16_f32 v2, v65, s0
	ds_write_b16 v1, v2 offset:528
	v_cvt_pk_bf16_f32 v2, v66, s0
	ds_write_b16 v1, v2 offset:1056
	v_cvt_pk_bf16_f32 v2, v67, s0
	ds_write_b16 v1, v2 offset:1584
	v_cvt_pk_bf16_f32 v2, v68, s0
	ds_write_b16 v1, v2 offset:4224
	v_cvt_pk_bf16_f32 v2, v69, s0
	ds_write_b16 v1, v2 offset:4752
	v_cvt_pk_bf16_f32 v2, v70, s0
	ds_write_b16 v1, v2 offset:5280
	v_cvt_pk_bf16_f32 v2, v71, s0
	ds_write_b16 v1, v2 offset:5808
	v_cvt_pk_bf16_f32 v2, v72, s0
	ds_write_b16 v1, v2 offset:8448
	v_cvt_pk_bf16_f32 v2, v73, s0
	ds_write_b16 v1, v2 offset:8976
	v_cvt_pk_bf16_f32 v2, v74, s0
	ds_write_b16 v1, v2 offset:9504
	v_cvt_pk_bf16_f32 v2, v75, s0
	ds_write_b16 v1, v2 offset:10032
	v_cvt_pk_bf16_f32 v2, v76, s0
	ds_write_b16 v1, v2 offset:12672
	v_cvt_pk_bf16_f32 v2, v77, s0
	ds_write_b16 v1, v2 offset:13200
	v_cvt_pk_bf16_f32 v2, v78, s0
	ds_write_b16 v1, v2 offset:13728
	v_cvt_pk_bf16_f32 v2, v79, s0
	ds_write_b16 v1, v2 offset:14256
	v_cvt_pk_bf16_f32 v2, v48, s0
	ds_write_b16 v1, v2 offset:64
	v_cvt_pk_bf16_f32 v2, v49, s0
	ds_write_b16 v1, v2 offset:592
	v_cvt_pk_bf16_f32 v2, v50, s0
	ds_write_b16 v1, v2 offset:1120
	v_cvt_pk_bf16_f32 v2, v51, s0
	ds_write_b16 v1, v2 offset:1648
	v_cvt_pk_bf16_f32 v2, v52, s0
	ds_write_b16 v1, v2 offset:4288
	v_cvt_pk_bf16_f32 v2, v53, s0
	ds_write_b16 v1, v2 offset:4816
	v_cvt_pk_bf16_f32 v2, v54, s0
	ds_write_b16 v1, v2 offset:5344
	v_cvt_pk_bf16_f32 v2, v55, s0
	ds_write_b16 v1, v2 offset:5872
	v_cvt_pk_bf16_f32 v2, v56, s0
	ds_write_b16 v1, v2 offset:8512
	v_cvt_pk_bf16_f32 v2, v57, s0
	ds_write_b16 v1, v2 offset:9040
	v_cvt_pk_bf16_f32 v2, v58, s0
	ds_write_b16 v1, v2 offset:9568
	v_cvt_pk_bf16_f32 v2, v59, s0
	ds_write_b16 v1, v2 offset:10096
	v_cvt_pk_bf16_f32 v2, v60, s0
	ds_write_b16 v1, v2 offset:12736
	v_cvt_pk_bf16_f32 v2, v61, s0
	ds_write_b16 v1, v2 offset:13264
	v_cvt_pk_bf16_f32 v2, v62, s0
	ds_write_b16 v1, v2 offset:13792
	v_cvt_pk_bf16_f32 v2, v63, s0
	ds_write_b16 v1, v2 offset:14320
	v_cvt_pk_bf16_f32 v2, v32, s0
	ds_write_b16 v1, v2 offset:16896
	v_cvt_pk_bf16_f32 v2, v33, s0
	ds_write_b16 v1, v2 offset:17424
	v_cvt_pk_bf16_f32 v2, v34, s0
	ds_write_b16 v1, v2 offset:17952
	v_cvt_pk_bf16_f32 v2, v35, s0
	ds_write_b16 v1, v2 offset:18480
	v_cvt_pk_bf16_f32 v2, v36, s0
	ds_write_b16 v1, v2 offset:21120
	v_cvt_pk_bf16_f32 v2, v37, s0
	ds_write_b16 v1, v2 offset:21648
	v_cvt_pk_bf16_f32 v2, v38, s0
	ds_write_b16 v1, v2 offset:22176
	v_cvt_pk_bf16_f32 v2, v39, s0
	ds_write_b16 v1, v2 offset:22704
	v_cvt_pk_bf16_f32 v2, v40, s0
	ds_write_b16 v1, v2 offset:25344
	v_cvt_pk_bf16_f32 v2, v41, s0
	ds_write_b16 v1, v2 offset:25872
	v_cvt_pk_bf16_f32 v2, v42, s0
	ds_write_b16 v1, v2 offset:26400
	v_cvt_pk_bf16_f32 v2, v43, s0
	ds_write_b16 v1, v2 offset:26928
	v_cvt_pk_bf16_f32 v2, v44, s0
	ds_write_b16 v1, v2 offset:29568
	v_cvt_pk_bf16_f32 v2, v45, s0
	ds_write_b16 v1, v2 offset:30096
	v_cvt_pk_bf16_f32 v2, v46, s0
	ds_write_b16 v1, v2 offset:30624
	v_cvt_pk_bf16_f32 v2, v47, s0
	ds_write_b16 v1, v2 offset:31152
	v_cvt_pk_bf16_f32 v2, v16, s0
	ds_write_b16 v1, v2 offset:16960
	v_cvt_pk_bf16_f32 v2, v17, s0
	ds_write_b16 v1, v2 offset:17488
	v_cvt_pk_bf16_f32 v2, v18, s0
	ds_write_b16 v1, v2 offset:18016
	v_cvt_pk_bf16_f32 v2, v19, s0
	ds_write_b16 v1, v2 offset:18544
	v_cvt_pk_bf16_f32 v2, v20, s0
	ds_write_b16 v1, v2 offset:21184
	v_cvt_pk_bf16_f32 v2, v21, s0
	ds_write_b16 v1, v2 offset:21712
	v_cvt_pk_bf16_f32 v2, v22, s0
	ds_write_b16 v1, v2 offset:22240
	v_cvt_pk_bf16_f32 v2, v23, s0
	ds_write_b16 v1, v2 offset:22768
	v_cvt_pk_bf16_f32 v2, v24, s0
	ds_write_b16 v1, v2 offset:25408
	v_cvt_pk_bf16_f32 v2, v25, s0
	ds_write_b16 v1, v2 offset:25936
	v_cvt_pk_bf16_f32 v2, v26, s0
	ds_write_b16 v1, v2 offset:26464
	v_cvt_pk_bf16_f32 v2, v27, s0
	ds_write_b16 v1, v2 offset:26992
	v_cvt_pk_bf16_f32 v2, v28, s0
	ds_write_b16 v1, v2 offset:29632
	v_cvt_pk_bf16_f32 v2, v29, s0
	ds_write_b16 v1, v2 offset:30160
	v_cvt_pk_bf16_f32 v2, v30, s0
	s_add_i32 s29, s29, 1
	v_cvt_pk_bf16_f32 v4, v64, s0
	ds_write_b16 v1, v2 offset:30688
	v_cvt_pk_bf16_f32 v2, v31, s0
	s_cmp_eq_u32 s29, 16
	ds_write_b16 v1, v4
	ds_write_b16 v1, v2 offset:31216
	s_cbranch_scc0 .LBB0_1194
	s_mov_b32 s0, 1
	s_mov_b64 s[16:17], 0
	s_and_b64 vcc, exec, s[18:19]
	s_waitcnt lgkmcnt(0)
	s_barrier
	s_cbranch_vccz .LBB0_1182
	s_add_i32 s24, s24, s74
	s_cmpk_lt_i32 s24, 0x100
	s_cbranch_scc1 .LBB0_1173

.LBB0_2212:
	s_andn2_b64 vcc, exec, s[0:1]
	s_cbranch_vccnz .LBB0_2214
	v_add_u32_e32 v203, s72, v172
	v_add_u32_e32 v248, 0xffffff80, v203
	v_add_u32_e32 v247, 0xffffff81, v203
	v_add_u32_e32 v246, 0xffffff82, v203
	v_add_u32_e32 v245, 0xffffff83, v203
	v_add_u32_e32 v244, 0xffffff88, v203
	v_add_u32_e32 v243, 0xffffff89, v203
	v_add_u32_e32 v242, 0xffffff8a, v203
	v_add_u32_e32 v241, 0xffffff8b, v203
	v_add_u32_e32 v240, 0xffffff90, v203
	v_add_u32_e32 v239, 0xffffff91, v203
	v_add_u32_e32 v238, 0xffffff92, v203
	v_add_u32_e32 v237, 0xffffff93, v203
	v_add_u32_e32 v236, 0xffffff98, v203
	v_add_u32_e32 v235, 0xffffff99, v203
	v_add_u32_e32 v234, 0xffffff9a, v203
	v_add_u32_e32 v233, 0xffffff9b, v203
	v_add_u32_e32 v232, 0xffffffa0, v203
	v_add_u32_e32 v231, 0xffffffa1, v203
	v_add_u32_e32 v230, 0xffffffa2, v203
	v_add_u32_e32 v229, 0xffffffa3, v203
	v_add_u32_e32 v228, 0xffffffa8, v203
	v_add_u32_e32 v227, 0xffffffa9, v203
	v_add_u32_e32 v226, 0xffffffaa, v203
	v_add_u32_e32 v225, 0xffffffab, v203
	v_add_u32_e32 v224, 0xffffffb0, v203
	v_add_u32_e32 v223, 0xffffffb1, v203
	v_add_u32_e32 v209, 0xffffffb2, v203
	v_add_u32_e32 v208, 0xffffffb3, v203
	v_add_u32_e32 v207, 0xffffffb8, v203
	v_add_u32_e32 v206, 0xffffffb9, v203
	v_add_u32_e32 v205, 0xffffffba, v203
	v_add_u32_e32 v203, 0xffffffbb, v203
	v_cmp_gt_i32_e64 s[64:65], s71, v248
	v_add_u32_e32 v204, s79, v188
	v_cmp_gt_i32_e64 s[62:63], s71, v247
	v_cmp_gt_i32_e64 s[60:61], s71, v246
	v_cmp_gt_i32_e64 s[58:59], s71, v245
	v_cmp_gt_i32_e64 s[56:57], s71, v244
	v_cmp_gt_i32_e64 s[54:55], s71, v243
	v_cmp_gt_i32_e64 s[52:53], s71, v242
	v_cmp_gt_i32_e64 s[50:51], s71, v241
	v_cmp_gt_i32_e64 s[48:49], s71, v240
	v_cmp_gt_i32_e64 s[46:47], s71, v239
	v_cmp_gt_i32_e64 s[44:45], s71, v238
	v_cmp_gt_i32_e64 s[42:43], s71, v237
	v_cmp_gt_i32_e64 s[40:41], s71, v236
	v_cmp_gt_i32_e64 s[38:39], s71, v235
	v_cmp_gt_i32_e64 s[36:37], s71, v234
	v_cmp_gt_i32_e64 s[34:35], s71, v233
	v_cmp_gt_i32_e64 s[30:31], s71, v232
	v_cmp_gt_i32_e64 s[28:29], s71, v231
	v_cmp_gt_i32_e64 s[26:27], s71, v230
	v_cmp_gt_i32_e64 s[24:25], s71, v229
	v_cmp_gt_i32_e64 s[22:23], s71, v228
	v_cmp_gt_i32_e64 s[20:21], s71, v227
	v_cmp_gt_i32_e64 s[18:19], s71, v226
	v_cmp_gt_i32_e64 s[16:17], s71, v225
	v_cmp_gt_i32_e64 s[14:15], s71, v224
	v_cmp_gt_i32_e64 s[12:13], s71, v223
	v_cmp_gt_i32_e64 s[10:11], s71, v209
	v_cmp_gt_i32_e64 s[8:9], s71, v208
	v_cmp_gt_i32_e64 s[6:7], s71, v207
	v_cmp_gt_i32_e64 s[4:5], s71, v206
	v_cmp_gt_i32_e64 s[66:67], s71, v205
	v_cmp_gt_i32_e64 s[0:1], s71, v203
	v_add_u32_e32 v201, 0x100, v204
	v_cmp_gt_u32_e32 vcc, s75, v201
	s_and_b64 s[64:65], s[86:87], s[64:65]
	s_and_b64 vcc, s[64:65], vcc
	v_add_u32_e32 v201, 0xff, v204
	v_cndmask_b32_e32 v114, v221, v114, vcc
	v_cmp_gt_u32_e32 vcc, s75, v201
	s_and_b64 s[62:63], s[86:87], s[62:63]
	s_and_b64 vcc, s[62:63], vcc
	v_add_u32_e32 v212, 0xfe, v204
	v_cndmask_b32_e32 v115, v221, v115, vcc
	v_cmp_gt_u32_e32 vcc, s75, v212
	s_and_b64 s[60:61], s[86:87], s[60:61]
	s_and_b64 vcc, s[60:61], vcc
	v_add_u32_e32 v212, 0xfd, v204
	v_cndmask_b32_e32 v116, v221, v116, vcc
	v_cmp_gt_u32_e32 vcc, s75, v212
	s_and_b64 s[58:59], s[86:87], s[58:59]
	s_and_b64 vcc, s[58:59], vcc
	v_add_u32_e32 v212, 0xf8, v204
	v_cndmask_b32_e32 v117, v221, v117, vcc
	v_cmp_gt_u32_e32 vcc, s75, v212
	s_and_b64 s[56:57], s[86:87], s[56:57]
	s_and_b64 vcc, s[56:57], vcc
	v_add_u32_e32 v212, 0xf7, v204
	v_cndmask_b32_e32 v118, v221, v118, vcc
	v_cmp_gt_u32_e32 vcc, s75, v212
	s_and_b64 s[54:55], s[86:87], s[54:55]
	s_and_b64 vcc, s[54:55], vcc
	v_add_u32_e32 v212, 0xf6, v204
	v_cndmask_b32_e32 v119, v221, v119, vcc
	v_cmp_gt_u32_e32 vcc, s75, v212
	s_and_b64 s[52:53], s[86:87], s[52:53]
	s_and_b64 vcc, s[52:53], vcc
	v_add_u32_e32 v212, 0xf5, v204
	v_cndmask_b32_e32 v120, v221, v120, vcc
	v_cmp_gt_u32_e32 vcc, s75, v212
	s_and_b64 s[50:51], s[86:87], s[50:51]
	s_and_b64 vcc, s[50:51], vcc
	v_add_u32_e32 v212, 0xf0, v204
	v_cndmask_b32_e32 v121, v221, v121, vcc
	v_cmp_gt_u32_e32 vcc, s75, v212
	s_and_b64 s[48:49], s[86:87], s[48:49]
	s_and_b64 vcc, s[48:49], vcc
	v_add_u32_e32 v212, 0xef, v204
	v_cndmask_b32_e32 v122, v221, v122, vcc
	v_cmp_gt_u32_e32 vcc, s75, v212
	s_and_b64 s[46:47], s[86:87], s[46:47]
	s_and_b64 vcc, s[46:47], vcc
	v_add_u32_e32 v212, 0xee, v204
	v_cndmask_b32_e32 v123, v221, v123, vcc
	v_cmp_gt_u32_e32 vcc, s75, v212
	s_and_b64 s[44:45], s[86:87], s[44:45]
	s_and_b64 vcc, s[44:45], vcc
	v_add_u32_e32 v212, 0xed, v204
	v_cndmask_b32_e32 v124, v221, v124, vcc
	v_cmp_gt_u32_e32 vcc, s75, v212
	s_and_b64 s[42:43], s[86:87], s[42:43]
	s_and_b64 vcc, s[42:43], vcc
	v_add_u32_e32 v212, 0xe8, v204
	v_cndmask_b32_e32 v125, v221, v125, vcc
	v_cmp_gt_u32_e32 vcc, s75, v212
	s_and_b64 s[40:41], s[86:87], s[40:41]
	s_and_b64 vcc, s[40:41], vcc
	v_add_u32_e32 v212, 0xe7, v204
	v_cndmask_b32_e32 v126, v221, v126, vcc
	v_cmp_gt_u32_e32 vcc, s75, v212
	s_and_b64 s[38:39], s[86:87], s[38:39]
	s_and_b64 vcc, s[38:39], vcc
	v_add_u32_e32 v212, 0xe6, v204
	v_cndmask_b32_e32 v127, v221, v127, vcc
	v_cmp_gt_u32_e32 vcc, s75, v212
	s_and_b64 s[36:37], s[86:87], s[36:37]
	s_and_b64 vcc, s[36:37], vcc
	v_add_u32_e32 v212, 0xe5, v204
	v_cndmask_b32_e32 v128, v221, v128, vcc
	v_cmp_gt_u32_e32 vcc, s75, v212
	s_and_b64 s[34:35], s[86:87], s[34:35]
	s_and_b64 vcc, s[34:35], vcc
	v_add_u32_e32 v212, 0xe0, v204
	v_cndmask_b32_e32 v129, v221, v129, vcc
	v_cmp_gt_u32_e32 vcc, s75, v212
	s_and_b64 s[30:31], s[86:87], s[30:31]
	s_and_b64 vcc, s[30:31], vcc
	v_add_u32_e32 v212, 0xdf, v204
	v_cndmask_b32_e32 v98, v221, v98, vcc
	v_cmp_gt_u32_e32 vcc, s75, v212
	s_and_b64 s[28:29], s[86:87], s[28:29]
	s_and_b64 vcc, s[28:29], vcc
	v_add_u32_e32 v212, 0xde, v204
	v_cndmask_b32_e32 v99, v221, v99, vcc
	v_cmp_gt_u32_e32 vcc, s75, v212
	s_and_b64 s[26:27], s[86:87], s[26:27]
	s_and_b64 vcc, s[26:27], vcc
	v_add_u32_e32 v212, 0xdd, v204
	v_cndmask_b32_e32 v100, v221, v100, vcc
	v_cmp_gt_u32_e32 vcc, s75, v212
	s_and_b64 s[24:25], s[86:87], s[24:25]
	s_and_b64 vcc, s[24:25], vcc
	v_add_u32_e32 v212, 0xd8, v204
	v_cndmask_b32_e32 v101, v221, v101, vcc
	v_cmp_gt_u32_e32 vcc, s75, v212
	s_and_b64 s[22:23], s[86:87], s[22:23]
	s_and_b64 vcc, s[22:23], vcc
	v_add_u32_e32 v212, 0xd7, v204
	v_cndmask_b32_e32 v102, v221, v102, vcc
	v_cmp_gt_u32_e32 vcc, s75, v212
	s_and_b64 s[20:21], s[86:87], s[20:21]
	s_and_b64 vcc, s[20:21], vcc
	v_add_u32_e32 v212, 0xd6, v204
	v_cndmask_b32_e32 v103, v221, v103, vcc
	v_cmp_gt_u32_e32 vcc, s75, v212
	s_and_b64 s[18:19], s[86:87], s[18:19]
	s_and_b64 vcc, s[18:19], vcc
	v_add_u32_e32 v212, 0xd5, v204
	v_cndmask_b32_e32 v104, v221, v104, vcc
	v_cmp_gt_u32_e32 vcc, s75, v212
	s_and_b64 s[16:17], s[86:87], s[16:17]
	s_and_b64 vcc, s[16:17], vcc
	v_add_u32_e32 v212, 0xd0, v204
	v_cndmask_b32_e32 v105, v221, v105, vcc
	v_cmp_gt_u32_e32 vcc, s75, v212
	s_and_b64 s[14:15], s[86:87], s[14:15]
	s_mov_b32 s62, 0xf149f2ca
	s_and_b64 vcc, s[14:15], vcc
	v_add_u32_e32 v212, 0xcf, v204
	v_max3_f32 v201, v114, s62, v115
	v_cndmask_b32_e32 v106, v221, v106, vcc
	v_cmp_gt_u32_e32 vcc, s75, v212
	s_and_b64 s[12:13], s[86:87], s[12:13]
	v_max3_f32 v201, v201, v116, v117
	s_and_b64 vcc, s[12:13], vcc
	v_add_u32_e32 v212, 0xce, v204
	v_max3_f32 v201, v201, v118, v119
	v_cndmask_b32_e32 v107, v221, v107, vcc
	v_cmp_gt_u32_e32 vcc, s75, v212
	s_and_b64 s[10:11], s[86:87], s[10:11]
	v_max3_f32 v201, v201, v120, v121
	s_and_b64 vcc, s[10:11], vcc
	v_add_u32_e32 v212, 0xcd, v204
	v_max3_f32 v201, v201, v122, v123
	v_cndmask_b32_e32 v108, v221, v108, vcc
	v_cmp_gt_u32_e32 vcc, s75, v212
	s_and_b64 s[8:9], s[86:87], s[8:9]
	v_max3_f32 v201, v201, v124, v125
	s_and_b64 vcc, s[8:9], vcc
	v_add_u32_e32 v212, 0xc8, v204
	v_max3_f32 v201, v201, v126, v127
	v_cndmask_b32_e32 v109, v221, v109, vcc
	v_cmp_gt_u32_e32 vcc, s75, v212
	s_and_b64 s[6:7], s[86:87], s[6:7]
	v_max3_f32 v201, v201, v128, v129
	s_and_b64 vcc, s[6:7], vcc
	v_add_u32_e32 v212, 0xc7, v204
	v_max3_f32 v201, v201, v98, v99
	v_cndmask_b32_e32 v110, v221, v110, vcc
	v_cmp_gt_u32_e32 vcc, s75, v212
	s_and_b64 s[4:5], s[86:87], s[4:5]
	v_max3_f32 v201, v201, v100, v101
	s_and_b64 vcc, s[4:5], vcc
	v_add_u32_e32 v212, 0xc6, v204
	v_max3_f32 v201, v201, v102, v103
	v_cndmask_b32_e32 v111, v221, v111, vcc
	v_cmp_gt_u32_e32 vcc, s75, v212
	s_and_b64 s[4:5], s[86:87], s[66:67]
	v_max3_f32 v201, v201, v104, v105
	s_and_b64 vcc, s[4:5], vcc
	v_add_u32_e32 v212, 0xc5, v204
	v_max3_f32 v201, v201, v106, v107
	v_cndmask_b32_e32 v112, v221, v112, vcc
	v_cmp_gt_u32_e32 vcc, s75, v212
	s_and_b64 s[0:1], s[86:87], s[0:1]
	v_max3_f32 v201, v201, v108, v109
	s_and_b64 vcc, s[0:1], vcc
	v_max3_f32 v201, v201, v110, v111
	v_cndmask_b32_e32 v113, v221, v113, vcc
	v_max3_f32 v201, v201, v112, v113
